# static s_setprio 1 for waves 4-7 around the attention main loop (reset to 0 at loop exit), on top of wide O stores
# baseline (speedup 1.0000x reference)
; #define LAS __attribute__((address_space(3)))
; DI int v_st(int k, int c) { const int kk = (k & ~0xC) | ((k & 4) << 1) | ((k & 8) >> 1); return ((kk >> 3) * 4 + (c >> 5)) * 512 + ((kk & 7) * 32 + (c & 31)) * 2; }
; DI int v_rd_base(int lane) { return ((lane & 3) << 3) | (((lane >> 2) & 3) << 6) | (((lane >> 4) & 1) << 5) | (((lane >> 5) & 1) << 8); }
; #define SLOAD(k0) do { vs0 = *(const bf16x8*)(&Vh[(long)((k0) + sr) * LDK + sc]); vs1 = *(const bf16x8*)(&Vh[(long)((k0) + 32 + sr) * LDK + sc]); \
;     ks0 = *(const bf16x8*)(&Kh[(long)((k0) + sr) * LDK + sc]); ks1 = *(const bf16x8*)(&Kh[(long)((k0) + 32 + sr) * LDK + sc]); \
;     ps0 = *(const bf16x8*)(&Ph[(long)((k0) + pr) * LDP + pc]); } while (0)
; #define SWAIT() asm volatile("s_waitcnt vmcnt(0)" ::: "memory")
; DI void attn_unit(const bf16_t* __restrict__ Qb, const bf16_t* __restrict__ Kh, const bf16_t* __restrict__ Vh, const bf16_t* __restrict__ Ph,
;                   bf16_t* __restrict__ Ob, int seq, float* __restrict__ lse_out, char* lds) {
;     ...
;   int tid = threadIdx.x; asm volatile("" : "+v"(tid));
;   const int wid = tid >> 6, lane = tid & 63, r32 = lane & 31, hi = lane >> 5;
;   constexpr int A_STG = 40960, A_KO = 16384, A_PO = 32768;
;   float* wsf = (float*)(lds + 155648) + wid * 64; float* li_l = wsf; float* al_l = wsf + 32;
;   float m_reg = -1e30f, l_reg = 0; f32x16 o[4] = {}; bf16x8 qr[8];
;   char* QP = lds + 122880 + wid * 4096 + lane * 16;
;   const bf16_t* Qw = Qb + (long)(wid * 32 + r32) * LDQ + hi * 8;
; #pragma unroll
;   for (int d0 = 0; d0 < 8; ++d0) qr[d0] = *reinterpret_cast<const bf16x8*>(Qw + d0 * 16);
; #pragma unroll
;   for (int d0 = 0; d0 < 4; ++d0) *reinterpret_cast<bf16x8*>(QP + d0 * 1024) = *reinterpret_cast<const bf16x8*>(Qw + 128 + d0 * 16);
;   const int sr = tid >> 4, sc = (tid & 15) * 8, vst0 = v_st(sr, sc), vst1 = v_st(32 + sr, sc);
;   const int pr = tid >> 3, pc = (tid & 7) * 8;
;   const int vb0 = (int)(unsigned)(size_t)(LAS char*)lds + v_rd_base(lane);
;   bf16x8 vs0, vs1, ks0, ks1, ps0;
;     ...
;   f32x16 pA0, pA1, pB0, pB1; float mnA, mnB, alA, alB; bf16x8 pa0, pa1, pa2, pa3; const int NT = seq / 64;
;   SLOAD(0); SWAIT(); SWRITE(0); __syncthreads();
.LBB0_664:
	s_lshl_b32 s3, s6, 8
	s_ashr_i32 s6, s3, 31
	s_add_u32 s34, s4, s3
	s_addc_u32 s35, s5, s6
	s_add_i32 s20, s4, s2
	s_mul_i32 s2, s35, 0xc00
	s_mul_hi_u32 s3, s34, 0xc00
	s_add_i32 s3, s3, s2
	s_mul_i32 s2, s34, 0xc00
	v_mov_b32_e32 v54, v1
	s_add_u32 s4, s95, s2
	s_addc_u32 s5, s96, s3
	v_ashrrev_i32_e32 v55, 6, v54
	v_and_b32_e32 v159, 31, v54
	v_lshlrev_b32_e32 v136, 5, v55
	v_bfe_u32 v160, v54, 5, 1
	v_or_b32_e32 v138, v136, v159
	v_mov_b64_e32 v[2:3], s[4:5]
	s_movk_i32 s4, 0xc00
	v_mad_i64_i32 v[2:3], s[4:5], v138, s4, v[2:3]
	v_lshlrev_b32_e32 v134, 4, v160
	v_lshl_add_u64 v[42:43], v[2:3], 0, v[134:135]
	v_ashrrev_i32_e32 v50, 4, v54
	global_load_dwordx4 v[6:9], v[42:43], off offset:256
	global_load_dwordx4 v[10:13], v[42:43], off offset:288
	global_load_dwordx4 v[14:17], v[42:43], off offset:320
	global_load_dwordx4 v[18:21], v[42:43], off offset:352
	v_lshlrev_b32_e32 v56, 3, v54
	v_add_u32_e32 v44, 32, v50
	s_lshl_b64 s[2:3], s[20:21], 12
	v_and_b32_e32 v2, 0x78, v56
	v_ashrrev_i32_e32 v51, 31, v50
	v_ashrrev_i32_e32 v45, 31, v44
	s_add_u32 s2, s97, s2
	v_lshlrev_b32_e32 v57, 1, v2
	v_lshlrev_b64 v[2:3], 12, v[50:51]
	v_lshlrev_b64 v[4:5], 12, v[44:45]
	s_addc_u32 s3, s33, s3
	v_or_b32_e32 v2, v2, v57
	v_or_b32_e32 v4, v4, v57
	s_lshl_b64 s[36:37], s[20:21], 7
	v_ashrrev_i32_e32 v46, 3, v54
	v_lshl_add_u64 v[2:3], s[2:3], 0, v[2:3]
	v_lshl_add_u64 v[4:5], s[2:3], 0, v[4:5]
	s_add_u32 s2, s38, s36
	v_ashrrev_i32_e32 v47, 31, v46
	s_addc_u32 s3, s39, s37
	v_lshlrev_b64 v[52:53], 7, v[46:47]
	v_lshlrev_b32_e32 v45, 4, v54
	global_load_dwordx4 v[22:25], v[2:3], off offset:256
	global_load_dwordx4 v[26:29], v[4:5], off offset:256
	global_load_dwordx4 v[30:33], v[2:3], off
	global_load_dwordx4 v[34:37], v[4:5], off
	v_lshl_add_u64 v[4:5], s[2:3], 0, v[52:53]
	v_and_b32_e32 v48, 0x70, v45
	v_mov_b32_e32 v49, v135
	v_lshl_add_u64 v[4:5], v[4:5], 0, v[48:49]
	global_load_dwordx4 v[38:41], v[4:5], off
	global_load_dwordx4 v[114:117], v[42:43], off
	global_load_dwordx4 v[118:121], v[42:43], off offset:32
	global_load_dwordx4 v[126:129], v[42:43], off offset:64
	global_load_dwordx4 v[122:125], v[42:43], off offset:96
	global_load_dwordx4 v[110:113], v[42:43], off offset:128
	global_load_dwordx4 v[106:109], v[42:43], off offset:160
	global_load_dwordx4 v[102:105], v[42:43], off offset:192
	global_load_dwordx4 v[98:101], v[42:43], off offset:224
	v_and_b32_e32 v84, 63, v54
	v_lshlrev_b32_e32 v80, 4, v84
	v_lshl_add_u32 v47, v55, 12, s52
	v_and_b32_e32 v49, 0xfffff0, v50
	v_lshlrev_b32_e32 v55, 1, v50
	v_lshrrev_b32_e32 v58, 1, v50
	v_and_b32_e32 v60, 3, v50
	v_add_u32_e32 v163, v47, v80
	v_and_or_b32 v47, v55, 8, v49
	v_and_or_b32 v49, v58, 4, v60
	v_and_b32_e32 v55, 0xfffff0, v44
	v_lshlrev_b32_e32 v58, 1, v44
	v_and_or_b32 v55, v58, 8, v55
	v_bfe_u32 v59, v56, 5, 2
	v_lshrrev_b32_e32 v55, 1, v55
	v_lshlrev_b32_e32 v49, 6, v49
	v_and_b32_e32 v60, 48, v57
	v_lshrrev_b32_e32 v47, 1, v47
	v_or_b32_e32 v47, v47, v59
	v_lshlrev_b32_e32 v47, 9, v47
	v_or3_b32 v164, v47, v49, v60
	v_or_b32_e32 v81, 64, v134
	v_or_b32_e32 v82, 0x60, v134
	v_lshlrev_b32_e32 v83, 7, v159
	v_and_b32_e32 v89, 0x70, v56
	v_bitop3_b32 v179, v134, v83, v89 bitop3:0xde
	s_mov_b64 s[2:3], 0x40000
	v_bitop3_b32 v181, v81, v83, v89 bitop3:0xde
	v_bitop3_b32 v182, v82, v83, v89 bitop3:0xde
	s_mov_b32 s4, 0
	v_lshl_add_u64 v[140:141], v[52:53], 0, s[36:37]
	s_mov_b32 s5, s4
	s_mov_b32 s6, s4
	s_waitcnt vmcnt(16)
	ds_write_b128 v163, v[6:9]
	s_waitcnt vmcnt(15)
	ds_write_b128 v163, v[10:13] offset:1024
	s_waitcnt vmcnt(14)
	ds_write_b128 v163, v[14:17] offset:2048
	s_waitcnt vmcnt(13)
	ds_write_b128 v163, v[18:21] offset:3072
	v_or_b32_e32 v6, v55, v59
	v_lshlrev_b32_e32 v6, 9, v6
	v_or3_b32 v165, v6, v49, v60
	v_lshlrev_b32_e32 v6, 8, v50
	v_and_b32_e32 v7, 0xf0, v54
	v_bitop3_b32 v167, v57, v6, v7 bitop3:0xde
	v_lshlrev_b32_e32 v6, 8, v44
	v_bitop3_b32 v168, v57, v6, v7 bitop3:0xde
	v_lshlrev_b32_e32 v6, 7, v46
	v_and_b32_e32 v7, 0x70, v54
	v_lshlrev_b32_e32 v14, 8, v159
	v_and_b32_e32 v15, 0xf0, v45
	v_bitop3_b32 v169, v48, v6, v7 bitop3:0xde
	v_bitop3_b32 v170, v134, v14, v15 bitop3:0xde
	v_add_u32_e32 v55, 0, v164
	v_add_u32_e32 v85, 0, v165
	v_add_u32_e32 v86, 0, v167
	v_add_u32_e32 v87, 0, v168
	v_add_u32_e32 v88, 0, v169
	v_add_u32_e32 v10, 0, v170
	s_waitcnt vmcnt(0)
	v_or_b32_e32 v60, 32, v134
	s_waitcnt vmcnt(12)
	ds_write_b128 v55, v[22:25]
	s_waitcnt vmcnt(11)
	ds_write_b128 v85, v[26:29]
	s_waitcnt vmcnt(10)
	ds_write_b128 v86, v[30:33] offset:16384
	s_waitcnt vmcnt(9)
	ds_write_b128 v87, v[34:37] offset:16384
	v_bitop3_b32 v172, v60, v14, v15 bitop3:0xde
	v_bitop3_b32 v173, v81, v14, v15 bitop3:0xde
	s_waitcnt vmcnt(8)
	ds_write_b128 v88, v[38:41] offset:32768
	s_waitcnt lgkmcnt(0)
	s_barrier
; #define MFMA32(a, b, c) __builtin_amdgcn_mfma_f32_32x32x16_bf16((a), (b), (c), 0, 0, 0)
; #define SLOAD(k0) do { vs0 = *(const bf16x8*)(&Vh[(long)((k0) + sr) * LDK + sc]); vs1 = *(const bf16x8*)(&Vh[(long)((k0) + 32 + sr) * LDK + sc]); \
;     ks0 = *(const bf16x8*)(&Kh[(long)((k0) + sr) * LDK + sc]); ks1 = *(const bf16x8*)(&Kh[(long)((k0) + 32 + sr) * LDK + sc]); \
;     ps0 = *(const bf16x8*)(&Ph[(long)((k0) + pr) * LDP + pc]); } while (0)
; #define SWRITE(st) do { char* b_ = lds + (st); *(bf16x8*)(b_ + vst0) = vs0; *(bf16x8*)(b_ + vst1) = vs1; const int kc = sc * 2; \
;     *(bf16x8*)(b_ + A_KO + KSWZ(sr, kc)) = ks0; *(bf16x8*)(b_ + A_KO + KSWZ(32 + sr, kc)) = ks1; \
;     *(bf16x8*)(b_ + A_PO + PSWZ(pr, pc * 2)) = ps0; } while (0)
; #define SWAIT() asm volatile("s_waitcnt vmcnt(0)" ::: "memory")
; DI void a_qkt(f32x16& p0, f32x16& p1, const char* Ks, const char* Ps, const bf16x8* qr, const char* QP, int r32, int hi) {
;   p0 = f32x16{}; p1 = f32x16{};
; #pragma unroll
;   for (int d0 = 0; d0 < 8; ++d0) { const int cb = (d0 * 16 + hi * 8) * 2;
;     bf16x8 b0 = *reinterpret_cast<const bf16x8*>(Ks + KSWZ(r32, cb));
;     bf16x8 b1 = *reinterpret_cast<const bf16x8*>(Ks + KSWZ(32 + r32, cb));
;     p0 = MFMA32(b0, qr[d0], p0);
;     p1 = MFMA32(b1, qr[d0], p1); }
; #pragma unroll
;   for (int d0 = 0; d0 < 4; ++d0) { const int cb = (d0 * 16 + hi * 8) * 2;
;     bf16x8 b0 = *reinterpret_cast<const bf16x8*>(Ps + PSWZ(r32, cb));
;     bf16x8 b1 = *reinterpret_cast<const bf16x8*>(Ps + PSWZ(32 + r32, cb));
;     const bf16x8 qp = *reinterpret_cast<const bf16x8*>(QP + d0 * 1024);
;     p0 = MFMA32(b0, qp, p0);
;     p1 = MFMA32(b1, qp, p1); }
; DI void attn_unit(const bf16_t* __restrict__ Qb, const bf16_t* __restrict__ Kh, const bf16_t* __restrict__ Vh, const bf16_t* __restrict__ Ph,
;                   bf16_t* __restrict__ Ob, int seq, float* __restrict__ lse_out, char* lds) {
;     ...
;   a_qkt(pA0, pA1, lds + A_KO, lds + A_PO, qr, QP, r32, hi); a_partialSM(pA0, pA1, m_reg, mnA, alA);
;   SLOAD(64);
;   SWAIT(); SWRITE(A_STG); __syncthreads();
	ds_read_b128 v[6:9], v10 offset:16384
	ds_read_b128 v[10:13], v10 offset:24576
	s_waitcnt vmcnt(7) lgkmcnt(1)
	v_mfma_f32_32x32x16_bf16 v[34:49], v[6:9], v[114:117], 0
	v_bitop3_b32 v174, v82, v14, v15 bitop3:0xde
	v_bitop3_b32 v180, v60, v83, v89 bitop3:0xde
	s_mov_b32 s7, s4
	s_mov_b32 s8, s4
	s_mov_b32 s9, s4
	s_mov_b32 s10, s4
	s_mov_b32 s11, s4
	s_waitcnt lgkmcnt(0)
	v_mfma_f32_32x32x16_bf16 v[18:33], v[10:13], v[114:117], 0
	v_add_u32_e32 v10, 0, v172
	ds_read_b128 v[6:9], v10 offset:16384
	ds_read_b128 v[10:13], v10 offset:24576
	s_mov_b32 s12, s4
	s_mov_b32 s13, s4
	s_mov_b32 s14, s4
	s_mov_b32 s15, s4
	s_mov_b32 s16, s4
	s_waitcnt vmcnt(6) lgkmcnt(1)
	v_mfma_f32_32x32x16_bf16 v[34:49], v[6:9], v[118:121], v[34:49]
	s_mov_b32 s17, s4
	s_mov_b32 s18, s4
	s_mov_b32 s19, s4
	s_mov_b32 s66, 2
	v_ashrrev_i32_e32 v139, 31, v138
	v_mov_b32_e32 v162, 0
	s_waitcnt lgkmcnt(0)
	v_mfma_f32_32x32x16_bf16 v[18:33], v[10:13], v[118:121], v[18:33]
	v_add_u32_e32 v10, 0, v173
	ds_read_b128 v[6:9], v10 offset:16384
	ds_read_b128 v[10:13], v10 offset:24576
	s_waitcnt vmcnt(5) lgkmcnt(1)
	v_mfma_f32_32x32x16_bf16 v[34:49], v[6:9], v[126:129], v[34:49]
	s_waitcnt lgkmcnt(0)
	v_mfma_f32_32x32x16_bf16 v[18:33], v[10:13], v[126:129], v[18:33]
	v_add_u32_e32 v10, 0, v174
	ds_read_b128 v[6:9], v10 offset:16384
	ds_read_b128 v[10:13], v10 offset:24576
	s_waitcnt vmcnt(4) lgkmcnt(1)
	v_mfma_f32_32x32x16_bf16 v[34:49], v[6:9], v[122:125], v[34:49]
	v_or_b32_e32 v6, 0x80, v134
	v_bitop3_b32 v175, v6, v14, v15 bitop3:0xde
	s_waitcnt lgkmcnt(0)
	v_mfma_f32_32x32x16_bf16 v[18:33], v[10:13], v[122:125], v[18:33]
	v_add_u32_e32 v10, 0, v175
	ds_read_b128 v[6:9], v10 offset:16384
	ds_read_b128 v[10:13], v10 offset:24576
	s_waitcnt vmcnt(3) lgkmcnt(1)
	v_mfma_f32_32x32x16_bf16 v[34:49], v[6:9], v[110:113], v[34:49]
	v_or_b32_e32 v6, 0xa0, v134
	v_bitop3_b32 v176, v6, v14, v15 bitop3:0xde
	s_waitcnt lgkmcnt(0)
	v_mfma_f32_32x32x16_bf16 v[18:33], v[10:13], v[110:113], v[18:33]
	v_add_u32_e32 v10, 0, v176
	ds_read_b128 v[6:9], v10 offset:16384
	ds_read_b128 v[10:13], v10 offset:24576
	s_waitcnt vmcnt(2) lgkmcnt(1)
	v_mfma_f32_32x32x16_bf16 v[34:49], v[6:9], v[106:109], v[34:49]
	v_or_b32_e32 v6, 0xc0, v134
	v_bitop3_b32 v177, v6, v14, v15 bitop3:0xde
	s_waitcnt lgkmcnt(0)
	v_mfma_f32_32x32x16_bf16 v[18:33], v[10:13], v[106:109], v[18:33]
	v_add_u32_e32 v10, 0, v177
	ds_read_b128 v[6:9], v10 offset:16384
	ds_read_b128 v[10:13], v10 offset:24576
	s_waitcnt vmcnt(1) lgkmcnt(1)
	v_mfma_f32_32x32x16_bf16 v[34:49], v[6:9], v[102:105], v[34:49]
	v_or_b32_e32 v6, 0xe0, v134
	v_bitop3_b32 v178, v6, v14, v15 bitop3:0xde
	v_add_u32_e32 v14, 0, v179
	s_waitcnt lgkmcnt(0)
	v_mfma_f32_32x32x16_bf16 v[18:33], v[10:13], v[102:105], v[18:33]
	v_add_u32_e32 v10, 0, v178
	ds_read_b128 v[6:9], v10 offset:16384
	ds_read_b128 v[10:13], v10 offset:24576
	s_waitcnt vmcnt(0) lgkmcnt(1)
	v_mfma_f32_32x32x16_bf16 v[34:49], v[6:9], v[98:101], v[34:49]
	s_waitcnt lgkmcnt(0)
	v_mfma_f32_32x32x16_bf16 v[18:33], v[10:13], v[98:101], v[18:33]
	ds_read_b128 v[6:9], v14 offset:32768
	ds_read_b128 v[10:13], v163
	ds_read_b128 v[14:17], v14 offset:36864
	ds_read_b128 v[56:59], v163 offset:1024
	s_waitcnt lgkmcnt(2)
	v_mfma_f32_32x32x16_bf16 v[34:49], v[6:9], v[10:13], v[34:49]
	s_waitcnt lgkmcnt(1)
	v_mfma_f32_32x32x16_bf16 v[18:33], v[14:17], v[10:13], v[18:33]
	v_lshl_add_u64 v[10:11], v[2:3], 0, s[2:3]
	s_mov_b64 s[2:3], 0x60000
	v_add_u32_e32 v14, 0, v180
	v_lshl_add_u64 v[12:13], v[2:3], 0, s[2:3]
	s_mov_b32 s2, 0x40000
	ds_read_b128 v[6:9], v14 offset:32768
	global_load_dwordx4 v[60:63], v[10:11], off offset:256
	global_load_dwordx4 v[64:67], v[12:13], off offset:256
	v_add_co_u32_e32 v10, vcc, s2, v2
	s_mov_b32 s2, 0x60000
	s_nop 0
	v_addc_co_u32_e32 v11, vcc, 0, v3, vcc
	v_add_co_u32_e32 v2, vcc, s2, v2
	s_waitcnt lgkmcnt(0)
	v_mfma_f32_32x32x16_bf16 v[34:49], v[6:9], v[56:59], v[34:49]
	v_addc_co_u32_e32 v3, vcc, 0, v3, vcc
	global_load_dwordx4 v[68:71], v[10:11], off
	global_load_dwordx4 v[72:75], v[2:3], off
	v_add_co_u32_e32 v2, vcc, s55, v4
	v_lshlrev_b32_e32 v10, 3, v84
	s_nop 0
	v_addc_co_u32_e32 v3, vcc, 0, v5, vcc
	global_load_dwordx4 v[76:79], v[2:3], off
	v_and_b32_e32 v2, 0x3fffffc0, v54
	v_lshl_add_u32 v137, v2, 2, s51
	ds_read_b128 v[2:5], v14 offset:36864
	v_and_b32_e32 v6, 0xc0, v80
	v_add_u32_e32 v13, 0, v181
	v_and_or_b32 v11, v10, 24, v6
	ds_read_b128 v[6:9], v13 offset:32768
	s_waitcnt lgkmcnt(1)
	v_mfma_f32_32x32x16_bf16 v[18:33], v[2:5], v[56:59], v[18:33]
	ds_read_b128 v[2:5], v163 offset:2048
	v_lshlrev_b32_e32 v12, 1, v54
	v_and_b32_e32 v12, 32, v12
	v_and_b32_e32 v10, 0x100, v10
	v_or3_b32 v10, v11, v12, v10
	v_add_u32_e32 v14, 0, v182
	v_add_u32_e32 v171, 0, v10
	ds_read_b128 v[10:13], v13 offset:36864
	ds_read_b128 v[56:59], v163 offset:3072
	s_waitcnt lgkmcnt(2)
	v_mfma_f32_32x32x16_bf16 v[34:49], v[6:9], v[2:5], v[34:49]
	ds_read_b128 v[6:9], v14 offset:32768
	ds_read_b128 v[80:83], v14 offset:36864
	s_waitcnt vmcnt(0)
	s_waitcnt vmcnt(4)
	ds_write_b128 v55, v[60:63] offset:40960
	s_waitcnt vmcnt(3)
	ds_write_b128 v85, v[64:67] offset:40960
	s_waitcnt vmcnt(2)
	ds_write_b128 v86, v[68:71] offset:57344
	s_waitcnt vmcnt(1)
	ds_write_b128 v87, v[72:75] offset:57344
	s_waitcnt lgkmcnt(7)
	v_mfma_f32_32x32x16_bf16 v[18:33], v[10:13], v[2:5], v[18:33]
	v_add_u32_e32 v55, 0x12000, v88
	v_cmp_gt_u32_e64 s[2:3], 32, v84
	v_lshl_add_u32 v161, v159, 2, v137
	s_waitcnt vmcnt(0)
	ds_write_b128 v55, v[76:79]
	s_waitcnt lgkmcnt(0)
	s_barrier
; #define SLOAD(k0) do { vs0 = *(const bf16x8*)(&Vh[(long)((k0) + sr) * LDK + sc]); vs1 = *(const bf16x8*)(&Vh[(long)((k0) + 32 + sr) * LDK + sc]); \
;     ks0 = *(const bf16x8*)(&Kh[(long)((k0) + sr) * LDK + sc]); ks1 = *(const bf16x8*)(&Kh[(long)((k0) + 32 + sr) * LDK + sc]); \
;     ps0 = *(const bf16x8*)(&Ph[(long)((k0) + pr) * LDP + pc]); } while (0)
; #define SWRITE(st) do { char* b_ = lds + (st); *(bf16x8*)(b_ + vst0) = vs0; *(bf16x8*)(b_ + vst1) = vs1; const int kc = sc * 2; \
;     *(bf16x8*)(b_ + A_KO + KSWZ(sr, kc)) = ks0; *(bf16x8*)(b_ + A_KO + KSWZ(32 + sr, kc)) = ks1; \
;     *(bf16x8*)(b_ + A_PO + PSWZ(pr, pc * 2)) = ps0; } while (0)
; #define SWAIT() asm volatile("s_waitcnt vmcnt(0)" ::: "memory")
; DI void a_partialSM(f32x16& p0, f32x16& p1, float& m_reg, float& mn, float& alpha) {
;   float pmax = p0[0];
; #pragma unroll
;   for (int r = 1; r < 16; ++r) pmax = fmaxf(pmax, p0[r]);
; #pragma unroll
;   for (int r = 0; r < 16; ++r) pmax = fmaxf(pmax, p1[r]);
;   { auto rr = __builtin_amdgcn_permlane32_swap(__float_as_uint(pmax), __float_as_uint(pmax), false, false);
;     pmax = fmaxf(__uint_as_float(rr[0]), __uint_as_float(rr[1])); }
;   if (__builtin_expect(__all(pmax - m_reg <= ATH), 1)) { mn = m_reg; alpha = 1.f; }
;   else { mn = fmaxf(m_reg, pmax); alpha = __builtin_amdgcn_exp2f(m_reg - mn); m_reg = mn; }
; #pragma unroll
;   for (int r = 0; r < 16; ++r) p0[r] = p0[r] - mn;
; #pragma unroll
;   for (int r = 0; r < 16; ++r) p1[r] = p1[r] - mn;
; #pragma unroll
;   for (int r = 0; r < 16; ++r) p0[r] = __builtin_amdgcn_exp2f(p0[r]);
; }
; DI void attn_unit(const bf16_t* __restrict__ Qb, const bf16_t* __restrict__ Kh, const bf16_t* __restrict__ Vh, const bf16_t* __restrict__ Ph,
;                   bf16_t* __restrict__ Ob, int seq, float* __restrict__ lse_out, char* lds) {
;     ...
;   f32x16 pA0, pA1, pB0, pB1; float mnA, mnB, alA, alB; bf16x8 pa0, pa1, pa2, pa3; const int NT = seq / 64;
;   SLOAD(0); SWAIT(); SWRITE(0); __syncthreads();
;   a_qkt(pA0, pA1, lds + A_KO, lds + A_PO, qr, QP, r32, hi); a_partialSM(pA0, pA1, m_reg, mnA, alA);
;   SLOAD(64);
;   SWAIT(); SWRITE(A_STG); __syncthreads();
;   int sV = 0, sK = A_STG, sW = 2 * A_STG;
;   for (int j = 1; j + 1 < NT; j += 2) {
	v_mfma_f32_32x32x16_bf16 v[34:49], v[6:9], v[56:59], v[34:49]
	v_mov_b64_e32 v[2:3], s[4:5]
	v_mov_b64_e32 v[16:17], s[18:19]
	v_mov_b64_e32 v[4:5], s[6:7]
	v_mov_b64_e32 v[6:7], s[8:9]
	v_mov_b64_e32 v[8:9], s[10:11]
	v_mov_b64_e32 v[10:11], s[12:13]
	v_mov_b64_e32 v[12:13], s[14:15]
	v_mfma_f32_32x32x16_bf16 v[18:33], v[80:83], v[56:59], v[18:33]
	s_nop 3
	v_max_f32_e32 v56, v35, v35
	v_max_f32_e32 v57, v34, v34
	v_max_f32_e32 v56, v57, v56
	v_max3_f32 v56, v56, v36, v37
	v_max3_f32 v56, v56, v38, v39
	v_max3_f32 v56, v56, v40, v41
	v_max3_f32 v56, v56, v42, v43
	v_max3_f32 v56, v56, v44, v45
	v_max3_f32 v56, v56, v46, v47
	v_max3_f32 v56, v56, v48, v49
	v_max3_f32 v56, v56, v18, v19
	v_max3_f32 v56, v56, v20, v21
	v_max3_f32 v56, v56, v22, v23
	v_max3_f32 v56, v56, v24, v25
	v_max3_f32 v56, v56, v26, v27
	v_max3_f32 v56, v56, v28, v29
	v_max3_f32 v56, v56, v30, v31
	v_max3_f32 v56, v56, v32, v33
	v_mov_b32_e32 v57, v56
	s_nop 1
	v_permlane32_swap_b32_e32 v56, v57
	v_max_f32_e32 v57, v57, v57
	v_max_f32_e32 v56, v56, v56
	v_max_f32_e32 v56, v56, v57
	v_add_f32_e32 v57, 0x7149f2ca, v56
	v_cmp_ge_f32_e32 vcc, s54, v57
	s_cmp_eq_u64 vcc, exec
	v_max_f32_e32 v55, 0xf149f2ca, v56
	s_cselect_b64 vcc, -1, 0
	v_cndmask_b32_e32 v144, v55, v158, vcc
	v_sub_f32_e32 v34, v34, v144
	v_exp_f32_e32 v191, v34
	v_sub_f32_e32 v34, v35, v144
	v_exp_f32_e32 v192, v34
	v_sub_f32_e32 v34, v36, v144
	v_exp_f32_e32 v194, v34
	v_sub_f32_e32 v34, v37, v144
	v_exp_f32_e32 v196, v34
	v_sub_f32_e32 v34, v38, v144
	v_exp_f32_e32 v198, v34
	v_sub_f32_e32 v34, v39, v144
	v_exp_f32_e32 v200, v34
	v_sub_f32_e32 v34, v40, v144
	v_exp_f32_e32 v197, v34
	v_sub_f32_e32 v34, v41, v144
	v_exp_f32_e32 v199, v34
	v_sub_f32_e32 v34, v42, v144
	v_exp_f32_e32 v185, v34
	v_sub_f32_e32 v34, v43, v144
	v_exp_f32_e32 v186, v34
	v_sub_f32_e32 v34, v44, v144
	v_exp_f32_e32 v188, v34
	v_sub_f32_e32 v34, v45, v144
	v_exp_f32_e32 v190, v34
	v_sub_f32_e32 v34, v46, v144
	v_exp_f32_e32 v187, v34
	v_sub_f32_e32 v34, v47, v144
	v_sub_f32_e32 v35, 0xf149f2ca, v55
	v_exp_f32_e32 v189, v34
	v_sub_f32_e32 v34, v48, v144
	v_exp_f32_e32 v35, v35
	v_sub_f32_e32 v130, v18, v144
	v_and_b32_e32 v18, 7, v54
	v_exp_f32_e32 v193, v34
	v_sub_f32_e32 v34, v49, v144
	v_sub_f32_e32 v131, v19, v144
	v_lshl_or_b32 v140, v18, 4, v140
	v_lshl_add_u64 v[18:19], v[50:51], 0, s[20:21]
	v_exp_f32_e32 v195, v34
	v_sub_f32_e32 v146, v20, v144
	v_lshlrev_b64 v[18:19], 12, v[18:19]
	v_and_b32_e32 v20, 15, v54
	v_sub_f32_e32 v147, v21, v144
	v_or_b32_e32 v18, s91, v18
	v_lshlrev_b32_e32 v20, 4, v20
	v_mov_b32_e32 v21, v135
	v_mov_b64_e32 v[14:15], s[16:17]
	v_cndmask_b32_e64 v183, v35, 1.0, vcc
	v_sub_f32_e32 v132, v22, v144
	v_sub_f32_e32 v133, v23, v144
	v_sub_f32_e32 v148, v24, v144
	v_sub_f32_e32 v149, v25, v144
	v_sub_f32_e32 v150, v26, v144
	v_sub_f32_e32 v151, v27, v144
	v_sub_f32_e32 v154, v28, v144
	v_sub_f32_e32 v155, v29, v144
	v_sub_f32_e32 v152, v30, v144
	v_sub_f32_e32 v153, v31, v144
	v_sub_f32_e32 v156, v32, v144
	v_sub_f32_e32 v157, v33, v144
	v_lshl_add_u64 v[142:143], v[18:19], 0, v[20:21]
	v_mov_b64_e32 v[64:65], v[16:17]
	v_mov_b64_e32 v[48:49], v[16:17]
	v_mov_b64_e32 v[32:33], v[16:17]
	s_mov_b32 s7, 0xa000
	s_mov_b32 s6, 0x14000
	v_mov_b64_e32 v[62:63], v[14:15]
	v_mov_b64_e32 v[60:61], v[12:13]
	v_mov_b64_e32 v[58:59], v[10:11]
	v_mov_b64_e32 v[56:57], v[8:9]
	v_mov_b64_e32 v[54:55], v[6:7]
	v_mov_b64_e32 v[52:53], v[4:5]
	v_mov_b64_e32 v[50:51], v[2:3]
	v_mov_b64_e32 v[46:47], v[14:15]
	v_mov_b64_e32 v[44:45], v[12:13]
	v_mov_b64_e32 v[42:43], v[10:11]
	v_mov_b64_e32 v[40:41], v[8:9]
	v_mov_b64_e32 v[38:39], v[6:7]
	v_mov_b64_e32 v[36:37], v[4:5]
	v_mov_b64_e32 v[34:35], v[2:3]
	v_mov_b64_e32 v[30:31], v[14:15]
	v_mov_b64_e32 v[28:29], v[12:13]
	v_mov_b64_e32 v[26:27], v[10:11]
	v_mov_b64_e32 v[24:25], v[8:9]
	v_mov_b64_e32 v[22:23], v[6:7]
	v_mov_b64_e32 v[20:21], v[4:5]
	v_mov_b64_e32 v[18:19], v[2:3]
	v_cmp_lt_u32_e32 vcc, 0xff, v1
	s_nop 4
	s_cbranch_vccz .Lattn_prio_skip
	s_setprio 1
.Lattn_prio_skip:
	v_mov_b32_e32 v240, v191
	v_mov_b32_e32 v241, v192
	v_mov_b32_e32 v242, v194
	v_mov_b32_e32 v243, v196
	v_mov_b32_e32 v244, v198
	v_mov_b32_e32 v245, v200
	v_mov_b32_e32 v246, v197
	v_mov_b32_e32 v247, v199
	v_mov_b32_e32 v248, v185
	v_mov_b32_e32 v249, v186
	v_mov_b32_e32 v250, v188
	v_mov_b32_e32 v251, v190
	v_mov_b32_e32 v252, v187
	v_mov_b32_e32 v253, v189
	v_mov_b32_e32 v254, v193
	v_mov_b32_e32 v255, v195

; #define MFMA32(a, b, c) __builtin_amdgcn_mfma_f32_32x32x16_bf16((a), (b), (c), 0, 0, 0)
; #define SBAR() __builtin_amdgcn_sched_barrier(0)
; DI void a_finishSM(f32x16& p0, f32x16& p1, float alpha, float& l_reg, bf16x8& pa0, bf16x8& pa1, bf16x8& pa2, bf16x8& pa3) {
; #pragma unroll
;   for (int r = 0; r < 16; ++r) p1[r] = __builtin_amdgcn_exp2f(p1[r]);
;   float ps = 0;
; #pragma unroll
;   for (int r = 0; r < 16; ++r) ps += p0[r];
; #pragma unroll
;   for (int r = 0; r < 16; ++r) ps += p1[r];
;   { auto rr = __builtin_amdgcn_permlane32_swap(__float_as_uint(ps), __float_as_uint(ps), false, false);
;     ps = __uint_as_float(rr[0]) + __uint_as_float(rr[1]); }
;   l_reg = l_reg * alpha + ps;
;     ...
;   PK4(p0, 0, pa0); PK4(p0, 8, pa1); PK4(p1, 0, pa2); PK4(p1, 8, pa3);
;     ...
; }
; DI void a_qkt(f32x16& p0, f32x16& p1, const char* Ks, const char* Ps, const bf16x8* qr, const char* QP, int r32, int hi) {
;   p0 = f32x16{}; p1 = f32x16{};
; #pragma unroll
;   for (int d0 = 0; d0 < 8; ++d0) { const int cb = (d0 * 16 + hi * 8) * 2;
;     bf16x8 b0 = *reinterpret_cast<const bf16x8*>(Ks + KSWZ(r32, cb));
;     bf16x8 b1 = *reinterpret_cast<const bf16x8*>(Ks + KSWZ(32 + r32, cb));
;     p0 = MFMA32(b0, qr[d0], p0);
;     p1 = MFMA32(b1, qr[d0], p1); }
; #pragma unroll
;   for (int d0 = 0; d0 < 4; ++d0) { const int cb = (d0 * 16 + hi * 8) * 2;
;     bf16x8 b0 = *reinterpret_cast<const bf16x8*>(Ps + PSWZ(r32, cb));
;     bf16x8 b1 = *reinterpret_cast<const bf16x8*>(Ps + PSWZ(32 + r32, cb));
;     const bf16x8 qp = *reinterpret_cast<const bf16x8*>(QP + d0 * 1024);
;     p0 = MFMA32(b0, qp, p0);
;     p1 = MFMA32(b1, qp, p1); }
; DI void attn_unit(const bf16_t* __restrict__ Qb, const bf16_t* __restrict__ Kh, const bf16_t* __restrict__ Vh, const bf16_t* __restrict__ Ph,
;                   bf16_t* __restrict__ Ob, int seq, float* __restrict__ lse_out, char* lds) {
;     ...
;   SBAR(); a_qkt(pB0, pB1, lds + sK + A_KO, lds + sK + A_PO, qr, QP, r32, hi);
;   a_finishSM(pA0, pA1, alA, l_reg, pa0, pa1, pa2, pa3); SBAR();
.LBB0_675:
	s_setprio 0
	v_mov_b32_e32 v191, v240
	v_mov_b32_e32 v192, v241
	v_mov_b32_e32 v194, v242
	v_mov_b32_e32 v196, v243
	v_mov_b32_e32 v198, v244
	v_mov_b32_e32 v200, v245
	v_mov_b32_e32 v197, v246
	v_mov_b32_e32 v199, v247
	v_mov_b32_e32 v185, v248
	v_mov_b32_e32 v186, v249
	v_mov_b32_e32 v188, v250
	v_mov_b32_e32 v190, v251
	v_mov_b32_e32 v187, v252
	v_mov_b32_e32 v189, v253
	v_mov_b32_e32 v193, v254
	v_mov_b32_e32 v195, v255
	v_add_u32_e32 v70, s9, v170
	ds_read_b128 v[66:69], v70 offset:16384
	ds_read_b128 v[70:73], v70 offset:24576
	v_add_u32_e32 v140, s9, v172
	v_add_u32_e32 v164, s9, v178
	v_exp_f32_e32 v130, v130
	s_waitcnt lgkmcnt(1)
	v_mfma_f32_32x32x16_bf16 v[82:97], v[66:69], v[114:117], 0
	v_exp_f32_e32 v131, v131
	v_exp_f32_e32 v146, v146
	v_exp_f32_e32 v147, v147
	v_exp_f32_e32 v132, v132
	s_waitcnt lgkmcnt(0)
	v_mfma_f32_32x32x16_bf16 v[66:81], v[70:73], v[114:117], 0
	ds_read_b128 v[114:117], v140 offset:16384
	ds_read_b128 v[140:143], v140 offset:24576
	s_waitcnt lgkmcnt(1)
	v_mfma_f32_32x32x16_bf16 v[82:97], v[114:117], v[118:121], v[82:97]
	s_waitcnt lgkmcnt(0)
	v_mfma_f32_32x32x16_bf16 v[66:81], v[140:143], v[118:121], v[66:81]
	v_add_u32_e32 v118, s9, v173
	ds_read_b128 v[114:117], v118 offset:16384
	ds_read_b128 v[118:121], v118 offset:24576
	v_add_u32_e32 v140, s9, v177
	s_waitcnt lgkmcnt(1)
	v_mfma_f32_32x32x16_bf16 v[82:97], v[114:117], v[126:129], v[82:97]
	s_waitcnt lgkmcnt(0)
	v_mfma_f32_32x32x16_bf16 v[66:81], v[118:121], v[126:129], v[66:81]
	v_add_u32_e32 v118, s9, v174
	ds_read_b128 v[114:117], v118 offset:16384
	ds_read_b128 v[118:121], v118 offset:24576
	s_waitcnt lgkmcnt(1)
	v_mfma_f32_32x32x16_bf16 v[82:97], v[114:117], v[122:125], v[82:97]
	s_waitcnt lgkmcnt(0)
	v_mfma_f32_32x32x16_bf16 v[66:81], v[118:121], v[122:125], v[66:81]
	v_add_u32_e32 v118, s9, v175
	ds_read_b128 v[114:117], v118 offset:16384
	ds_read_b128 v[118:121], v118 offset:24576
	v_add_u32_e32 v122, s9, v176
	s_waitcnt lgkmcnt(1)
	v_mfma_f32_32x32x16_bf16 v[82:97], v[114:117], v[110:113], v[82:97]
	ds_read_b128 v[114:117], v122 offset:16384
	ds_read_b128 v[122:125], v122 offset:24576
	ds_read_b128 v[126:129], v140 offset:16384
	ds_read_b128 v[140:143], v140 offset:24576
	s_waitcnt lgkmcnt(4)
	v_mfma_f32_32x32x16_bf16 v[66:81], v[118:121], v[110:113], v[66:81]
	ds_read_b128 v[110:113], v164 offset:16384
	ds_read_b128 v[118:121], v164 offset:24576
	v_add_u32_e32 v164, s9, v179
	ds_read_b128 v[172:175], v164 offset:32768
	ds_read_b128 v[176:179], v164 offset:36864
	v_add_u32_e32 v164, s9, v180
	ds_read_b128 v[202:205], v164 offset:32768
	ds_read_b128 v[206:209], v164 offset:36864
	v_add_u32_e32 v164, s9, v181
	s_waitcnt lgkmcnt(9)
	v_mfma_f32_32x32x16_bf16 v[82:97], v[114:117], v[106:109], v[82:97]
	ds_read_b128 v[114:117], v163
	ds_read_b128 v[210:213], v163 offset:1024
	ds_read_b128 v[214:217], v164 offset:32768
	ds_read_b128 v[218:221], v164 offset:36864
	v_add_u32_e32 v164, s9, v182
	ds_read_b128 v[180:183], v164 offset:32768
	ds_read_b128 v[222:225], v164 offset:36864
	s_waitcnt lgkmcnt(14)
	v_mfma_f32_32x32x16_bf16 v[66:81], v[122:125], v[106:109], v[66:81]
	ds_read_b128 v[106:109], v163 offset:2048
	ds_read_b128 v[122:125], v163 offset:3072
	s_waitcnt lgkmcnt(14)
	v_mfma_f32_32x32x16_bf16 v[82:97], v[126:129], v[102:105], v[82:97]
	v_exp_f32_e32 v126, v133
	v_exp_f32_e32 v127, v148
	v_exp_f32_e32 v128, v149
	v_exp_f32_e32 v129, v150
	v_exp_f32_e32 v133, v151
	v_exp_f32_e32 v148, v154
	v_exp_f32_e32 v149, v155
	v_mfma_f32_32x32x16_bf16 v[66:81], v[140:143], v[102:105], v[66:81]
	v_add_f32_e32 v102, 0, v191
	v_add_f32_e32 v102, v192, v102
	v_add_f32_e32 v102, v194, v102
	v_add_f32_e32 v102, v196, v102
	v_add_f32_e32 v102, v198, v102
	v_add_f32_e32 v102, v200, v102
	v_add_f32_e32 v102, v197, v102
	s_waitcnt lgkmcnt(13)
	v_mfma_f32_32x32x16_bf16 v[82:97], v[110:113], v[98:101], v[82:97]
	v_add_f32_e32 v102, v199, v102
	v_add_f32_e32 v102, v185, v102
	v_add_f32_e32 v102, v186, v102
	v_exp_f32_e32 v140, v152
	v_exp_f32_e32 v141, v153
	v_exp_f32_e32 v142, v156
	v_exp_f32_e32 v143, v157
	s_waitcnt lgkmcnt(12)
	v_mfma_f32_32x32x16_bf16 v[66:81], v[118:121], v[98:101], v[66:81]
	v_add_f32_e32 v98, v188, v102
	v_add_f32_e32 v98, v190, v98
	v_add_f32_e32 v98, v187, v98
	v_add_f32_e32 v98, v189, v98
	v_add_f32_e32 v98, v193, v98
	v_add_f32_e32 v98, v195, v98
	v_add_f32_e32 v98, v130, v98
	s_waitcnt lgkmcnt(7)
	v_mfma_f32_32x32x16_bf16 v[82:97], v[172:175], v[114:117], v[82:97]
	v_add_f32_e32 v98, v131, v98
	v_add_f32_e32 v98, v146, v98
	v_add_f32_e32 v98, v147, v98
	v_add_f32_e32 v98, v132, v98
	v_add_f32_e32 v98, v126, v98
	v_add_f32_e32 v98, v127, v98
	v_add_f32_e32 v98, v128, v98
	v_mfma_f32_32x32x16_bf16 v[66:81], v[176:179], v[114:117], v[66:81]
	v_add_f32_e32 v98, v129, v98
	v_add_f32_e32 v98, v133, v98
	v_add_f32_e32 v98, v148, v98
	v_add_f32_e32 v98, v149, v98
	v_add_f32_e32 v98, v140, v98
	v_add_f32_e32 v98, v141, v98
	v_add_f32_e32 v98, v142, v98
	s_waitcnt lgkmcnt(6)
	v_mfma_f32_32x32x16_bf16 v[82:97], v[202:205], v[210:213], v[82:97]
	v_add_f32_e32 v99, v143, v98
	v_mov_b32_e32 v100, v99
	s_nop 1
	v_permlane32_swap_b32_e32 v99, v100
	v_cvt_pk_bf16_f32 v102, v191, v192
	v_cvt_pk_bf16_f32 v103, v194, v196
	v_cvt_pk_bf16_f32 v104, v198, v200
	v_mfma_f32_32x32x16_bf16 v[66:81], v[206:209], v[210:213], v[66:81]
	v_cvt_pk_bf16_f32 v105, v197, v199
	v_cvt_pk_bf16_f32 v110, v185, v186
	v_cvt_pk_bf16_f32 v111, v188, v190
	v_cvt_pk_bf16_f32 v112, v187, v189
	v_cvt_pk_bf16_f32 v113, v193, v195
	v_cvt_pk_bf16_f32 v114, v130, v131
	v_cvt_pk_bf16_f32 v115, v146, v147
	s_waitcnt lgkmcnt(1)
; #define RESC(a) do { if (__any((a) < 1.f)) { if (hi == 0) al_l[r32] = (a); asm volatile("s_waitcnt lgkmcnt(0)" ::: "memory"); \
;     _Pragma("unroll") for (int d = 0; d < 4; ++d) _Pragma("unroll") for (int r = 0; r < 16; ++r) o[d][r] *= al_l[crow(r, hi)]; } } while (0)
; DI void pv_sm(f32x16* o, int vb, bf16x8 pa0, bf16x8 pa1, bf16x8 pa2, bf16x8 pa3, f32x16& p0, f32x16& p1, float& m_reg, float& mn, float& alpha) {
;   PV_BLOCK(0)
;   float pm0 = p0[0];
; #pragma unroll
;   for (int r = 1; r < 16; ++r) pm0 = fmaxf(pm0, p0[r]);
;   PV_BLOCK(1)
;   float pmax = pm0;
; #pragma unroll
;   for (int r = 0; r < 16; ++r) pmax = fmaxf(pmax, p1[r]);
;   { auto rr = __builtin_amdgcn_permlane32_swap(__float_as_uint(pmax), __float_as_uint(pmax), false, false);
;     pmax = fmaxf(__uint_as_float(rr[0]), __uint_as_float(rr[1])); }
;   const bool keep = __all(pmax - m_reg <= ATH);
;   mn = keep ? m_reg : fmaxf(m_reg, pmax);
;   alpha = __builtin_amdgcn_exp2f(m_reg - mn);
;   m_reg = mn;
;   PV_BLOCK(2)
; #pragma unroll
;   for (int r = 0; r < 16; ++r) { p0[r] = p0[r] - mn; p1[r] = p1[r] - mn; }
;   PV_BLOCK(3)
; #pragma unroll
;   for (int r = 0; r < 16; ++r) p0[r] = __builtin_amdgcn_exp2f(p0[r]);
; }
; DI void attn_unit(const bf16_t* __restrict__ Qb, const bf16_t* __restrict__ Kh, const bf16_t* __restrict__ Vh, const bf16_t* __restrict__ Ph,
;                   bf16_t* __restrict__ Ob, int seq, float* __restrict__ lse_out, char* lds) {
;     ...
;   pv_sm(o, vb0 + sV, pa0, pa1, pa2, pa3, pB0, pB1, m_reg, mnB, alB);
;   __syncthreads(); RESC(alB);
	v_mfma_f32_32x32x16_bf16 v[82:97], v[214:217], v[106:109], v[82:97]
	v_cvt_pk_bf16_f32 v116, v132, v126
	v_cvt_pk_bf16_f32 v117, v127, v128
	v_permlane32_swap_b32_e32 v102, v104
	v_permlane32_swap_b32_e32 v103, v105
	v_permlane32_swap_b32_e32 v110, v112
	v_mfma_f32_32x32x16_bf16 v[66:81], v[218:221], v[106:109], v[66:81]
	v_cvt_pk_bf16_f32 v106, v129, v133
	v_cvt_pk_bf16_f32 v107, v148, v149
	v_cvt_pk_bf16_f32 v108, v140, v141
	v_cvt_pk_bf16_f32 v109, v142, v143
	v_permlane32_swap_b32_e32 v111, v113
	v_permlane32_swap_b32_e32 v114, v116
	s_waitcnt lgkmcnt(0)
	v_mfma_f32_32x32x16_bf16 v[82:97], v[180:183], v[122:125], v[82:97]
	v_permlane32_swap_b32_e32 v115, v117
	v_permlane32_swap_b32_e32 v106, v108
	v_permlane32_swap_b32_e32 v107, v109
	v_mfma_f32_32x32x16_bf16 v[66:81], v[222:225], v[122:125], v[66:81]
	v_add_u32_e32 v146, s6, v171
	ds_read_b64_tr_b16 v[118:119], v146 offset:0
	ds_read_b64_tr_b16 v[120:121], v146 offset:0x800
	ds_read_b64_tr_b16 v[122:123], v146 offset:0x1000
	ds_read_b64_tr_b16 v[124:125], v146 offset:0x1800
	ds_read_b64_tr_b16 v[126:127], v146 offset:0x2000
	ds_read_b64_tr_b16 v[128:129], v146 offset:0x2800
	ds_read_b64_tr_b16 v[130:131], v146 offset:0x3000
	ds_read_b64_tr_b16 v[132:133], v146 offset:0x3800
	s_waitcnt lgkmcnt(0)
	s_nop 0
	v_mfma_f32_32x32x16_bf16 v[2:17], v[102:105], v[118:121], v[2:17]
	ds_read_b64_tr_b16 v[118:119], v146 offset:0x200
	ds_read_b64_tr_b16 v[120:121], v146 offset:0xa00
	s_nop 4
	v_max_f32_e32 v98, v83, v83
	v_max_f32_e32 v101, v82, v82
	v_max_f32_e32 v98, v101, v98
	v_max3_f32 v98, v98, v84, v85
	v_max3_f32 v98, v98, v86, v87
	v_mfma_f32_32x32x16_bf16 v[2:17], v[110:113], v[122:125], v[2:17]
	ds_read_b64_tr_b16 v[122:123], v146 offset:0x1200
	ds_read_b64_tr_b16 v[124:125], v146 offset:0x1a00
	v_max3_f32 v98, v98, v88, v89
	v_max3_f32 v98, v98, v90, v91
	v_max3_f32 v98, v98, v92, v93
	v_max3_f32 v98, v98, v94, v95
	v_max3_f32 v98, v98, v96, v97
	v_mfma_f32_32x32x16_bf16 v[2:17], v[114:117], v[126:129], v[2:17]
	ds_read_b64_tr_b16 v[126:127], v146 offset:0x2200
	ds_read_b64_tr_b16 v[128:129], v146 offset:0x2a00
	ds_read_b64_tr_b16 v[140:141], v146 offset:0x3200
	ds_read_b64_tr_b16 v[142:143], v146 offset:0x3a00
	s_waitcnt lgkmcnt(0)
	v_mfma_f32_32x32x16_bf16 v[2:17], v[106:109], v[130:133], v[2:17]
	v_mfma_f32_32x32x16_bf16 v[50:65], v[102:105], v[118:121], v[50:65]
	v_max3_f32 v98, v98, v66, v67
	v_max3_f32 v98, v98, v68, v69
	v_max3_f32 v98, v98, v70, v71
	v_max3_f32 v98, v98, v72, v73
	v_max3_f32 v98, v98, v74, v75
	v_max3_f32 v98, v98, v76, v77
	v_max3_f32 v98, v98, v78, v79
	v_mfma_f32_32x32x16_bf16 v[50:65], v[110:113], v[122:125], v[50:65]
	v_max3_f32 v98, v98, v80, v81
	v_mov_b32_e32 v101, v98
	s_nop 1
	v_permlane32_swap_b32_e32 v98, v101
	v_max_f32_e32 v101, v101, v101
	v_max_f32_e32 v98, v98, v98
	v_max_f32_e32 v98, v98, v101
	v_mfma_f32_32x32x16_bf16 v[50:65], v[114:117], v[126:129], v[50:65]
	ds_read_b64_tr_b16 v[118:119], v146 offset:0x400
	v_sub_f32_e32 v101, v98, v144
	ds_read_b64_tr_b16 v[120:121], v146 offset:0xc00
	v_cmp_ge_f32_e32 vcc, s54, v101
	ds_read_b64_tr_b16 v[122:123], v146 offset:0x1400
	s_cmp_eq_u64 vcc, exec
	v_max_f32_e32 v101, v144, v144
	ds_read_b64_tr_b16 v[124:125], v146 offset:0x1c00
	v_mfma_f32_32x32x16_bf16 v[50:65], v[106:109], v[140:143], v[50:65]
	v_max_f32_e32 v98, v101, v98
	s_cselect_b64 vcc, -1, 0
	ds_read_b64_tr_b16 v[126:127], v146 offset:0x2400
	v_cndmask_b32_e32 v98, v98, v144, vcc
	ds_read_b64_tr_b16 v[128:129], v146 offset:0x2c00
	v_sub_f32_e32 v101, v144, v98
	ds_read_b64_tr_b16 v[130:131], v146 offset:0x3400
	v_exp_f32_e32 v101, v101
	ds_read_b64_tr_b16 v[132:133], v146 offset:0x3c00
	s_waitcnt lgkmcnt(0)
	v_mfma_f32_32x32x16_bf16 v[34:49], v[102:105], v[118:121], v[34:49]
	ds_read_b64_tr_b16 v[118:119], v146 offset:0x600
	ds_read_b64_tr_b16 v[120:121], v146 offset:0xe00
	v_mfma_f32_32x32x16_bf16 v[34:49], v[110:113], v[122:125], v[34:49]
	ds_read_b64_tr_b16 v[122:123], v146 offset:0x1600
	ds_read_b64_tr_b16 v[124:125], v146 offset:0x1e00
	v_mfma_f32_32x32x16_bf16 v[34:49], v[114:117], v[126:129], v[34:49]
	ds_read_b64_tr_b16 v[126:127], v146 offset:0x2600
	ds_read_b64_tr_b16 v[128:129], v146 offset:0x2e00
	ds_read_b64_tr_b16 v[140:141], v146 offset:0x3600
	ds_read_b64_tr_b16 v[142:143], v146 offset:0x3e00
	s_waitcnt lgkmcnt(0)
	v_mfma_f32_32x32x16_bf16 v[34:49], v[106:109], v[130:133], v[34:49]
	v_mfma_f32_32x32x16_bf16 v[18:33], v[102:105], v[118:121], v[18:33]
	v_cmp_gt_f32_e32 vcc, 1.0, v101
	s_barrier
	v_mfma_f32_32x32x16_bf16 v[18:33], v[110:113], v[122:125], v[18:33]
	v_mfma_f32_32x32x16_bf16 v[18:33], v[114:117], v[126:129], v[18:33]
	v_mfma_f32_32x32x16_bf16 v[18:33], v[106:109], v[140:143], v[18:33]
	s_cbranch_vccz .LBB0_679
	s_and_saveexec_b64 s[4:5], s[2:3]
	ds_write_b32 v161, v101 offset:128
	s_or_b64 exec, exec, s[4:5]
	s_waitcnt lgkmcnt(0)
	v_add_u32_e32 v114, v137, v134
	ds_read_b128 v[102:105], v114 offset:224
	ds_read_b128 v[106:109], v114 offset:192
	ds_read_b128 v[110:113], v114 offset:160
	ds_read_b128 v[114:117], v114 offset:128
	s_waitcnt lgkmcnt(3)
	v_pk_mul_f32 v[14:15], v[14:15], v[102:103]
	s_waitcnt lgkmcnt(2)
	v_pk_mul_f32 v[10:11], v[10:11], v[106:107]
	s_waitcnt lgkmcnt(1)
	v_pk_mul_f32 v[6:7], v[6:7], v[110:111]
	v_pk_mul_f32 v[16:17], v[16:17], v[104:105]
	v_pk_mul_f32 v[12:13], v[12:13], v[108:109]
	v_pk_mul_f32 v[8:9], v[8:9], v[112:113]
	s_waitcnt lgkmcnt(0)
	v_pk_mul_f32 v[4:5], v[4:5], v[116:117]
	v_pk_mul_f32 v[2:3], v[2:3], v[114:115]
	v_pk_mul_f32 v[62:63], v[62:63], v[102:103]
	v_pk_mul_f32 v[58:59], v[58:59], v[106:107]
	v_pk_mul_f32 v[54:55], v[54:55], v[110:111]
	v_pk_mul_f32 v[64:65], v[64:65], v[104:105]
	v_pk_mul_f32 v[60:61], v[60:61], v[108:109]
	v_pk_mul_f32 v[56:57], v[56:57], v[112:113]
	v_pk_mul_f32 v[52:53], v[52:53], v[116:117]
	v_pk_mul_f32 v[50:51], v[50:51], v[114:115]
	v_pk_mul_f32 v[46:47], v[46:47], v[102:103]
	v_pk_mul_f32 v[42:43], v[42:43], v[106:107]
	v_pk_mul_f32 v[38:39], v[38:39], v[110:111]
	v_pk_mul_f32 v[48:49], v[48:49], v[104:105]
	v_pk_mul_f32 v[44:45], v[44:45], v[108:109]
	v_pk_mul_f32 v[40:41], v[40:41], v[112:113]
	v_pk_mul_f32 v[36:37], v[36:37], v[116:117]
	v_pk_mul_f32 v[34:35], v[34:35], v[114:115]
	v_pk_mul_f32 v[30:31], v[30:31], v[102:103]
	v_pk_mul_f32 v[26:27], v[26:27], v[106:107]
	v_pk_mul_f32 v[22:23], v[22:23], v[110:111]
	v_pk_mul_f32 v[32:33], v[32:33], v[104:105]
	v_pk_mul_f32 v[28:29], v[28:29], v[108:109]
	v_pk_mul_f32 v[24:25], v[24:25], v[112:113]
	v_pk_mul_f32 v[20:21], v[20:21], v[116:117]
	v_pk_mul_f32 v[18:19], v[18:19], v[114:115]
